# gdn_prep: prefetch next conv section's activation rows into spare registers while the current section computes
# baseline (speedup 1.0000x reference)
.LBB0_760:
	s_lshr_b32 s2, s13, 2
	s_and_b32 s37, s13, 3
	v_mov_b32_e32 v106, v228
	s_bfe_u32 s8, s13, 0x60002
	s_lshl_b32 s5, s2, 6
	s_lshl_b32 s4, s37, 7
	s_cmp_lg_u32 s8, 0
	v_ashrrev_i32_e32 v104, 3, v106
	s_cselect_b64 s[8:9], -1, 0
	v_cmp_lt_i32_e32 vcc, 2, v104
	s_waitcnt vmcnt(0)
	v_add_u32_e32 v0, -3, v104
	s_or_b64 vcc, s[8:9], vcc
	v_cndmask_b32_e32 v0, 0, v0, vcc
	v_cndmask_b32_e64 v44, 0, 1.0, vcc
	v_cmp_lt_i32_e32 vcc, 1, v104
	v_add_u32_e32 v4, -2, v104
	s_or_b64 vcc, s[8:9], vcc
	v_cndmask_b32_e32 v4, 0, v4, vcc
	v_cndmask_b32_e64 v42, 0, 1.0, vcc
	v_cmp_lt_i32_e32 vcc, 0, v104
	v_add_u32_e32 v8, -1, v104
	s_or_b64 vcc, s[8:9], vcc
	v_cndmask_b32_e32 v8, 0, v8, vcc
	v_cndmask_b32_e64 v40, 0, 1.0, vcc
	v_cmp_lt_i32_e32 vcc, -1, v104
	s_movk_i32 s2, 0x110
	s_or_b64 vcc, s[8:9], vcc
	v_and_b32_e32 v105, 7, v106
	v_mul_lo_u32 v109, v104, s2
	s_movk_i32 s2, 0x410
	v_cndmask_b32_e32 v14, 0, v104, vcc
	v_lshlrev_b32_e32 v108, 4, v105
	v_mul_lo_u32 v1, v104, s2
	v_add_u32_e32 v0, s5, v0
	v_mov_b64_e32 v[12:13], s[94:95]
	v_add_u32_e32 v4, s5, v4
	v_add_u32_e32 v8, s5, v8
	v_add_u32_e32 v14, s5, v14
	v_add_u32_e32 v107, 0, v1
	v_or_b32_e32 v39, s4, v108
	v_mad_i64_i32 v[0:1], s[38:39], v0, s66, v[12:13]
	v_mad_i64_i32 v[4:5], s[38:39], v4, s66, v[12:13]
	v_mad_i64_i32 v[8:9], s[38:39], v8, s66, v[12:13]
	v_mad_i64_i32 v[12:13], s[8:9], v14, s66, v[12:13]
	v_lshl_add_u64 v[46:47], v[0:1], 0, s[26:27]
	v_lshlrev_b32_e32 v16, 1, v39
	v_lshl_add_u64 v[48:49], v[4:5], 0, s[26:27]
	v_lshl_add_u64 v[50:51], v[8:9], 0, s[26:27]
	v_lshl_add_u64 v[52:53], v[12:13], 0, s[26:27]
	v_lshl_add_u64 v[0:1], v[46:47], 0, v[16:17]
	v_lshl_add_u64 v[4:5], v[48:49], 0, v[16:17]
	v_lshl_add_u64 v[8:9], v[50:51], 0, v[16:17]
	v_lshl_add_u64 v[12:13], v[52:53], 0, v[16:17]
	global_load_dwordx4 v[30:33], v[0:1], off
	s_nop 0
	global_load_dwordx4 v[0:3], v[0:1], off offset:16
	s_nop 0
	global_load_dwordx4 v[26:29], v[4:5], off
	s_nop 0
	global_load_dwordx4 v[4:7], v[4:5], off offset:16
	s_nop 0
	global_load_dwordx4 v[22:25], v[8:9], off
	s_nop 0
	global_load_dwordx4 v[8:11], v[8:9], off offset:16
	s_nop 0
	global_load_dwordx4 v[18:21], v[12:13], off
	s_nop 0
	global_load_dwordx4 v[12:15], v[12:13], off offset:16
	s_mov_b32 s8, 0
	s_ashr_i32 s9, s8, 31
	s_lshl_b64 s[8:9], s[8:9], 3
	s_add_u32 s8, s0, s8
	s_addc_u32 s9, s1, s9
	s_load_dwordx2 s[98:99], s[0:1], 0x98
	s_load_dwordx2 s[100:101], s[0:1], 0xa0
	s_load_dwordx2 s[8:9], s[8:9], 0x90
	v_lshlrev_b32_e32 v41, 2, v39
	v_cndmask_b32_e64 v38, 0, 1.0, vcc
	v_and_b32_e32 v111, 64, v234
	v_or_b32_e32 v16, 0x400, v16
	s_waitcnt lgkmcnt(0)
	v_or_b32_e32 v188, s5, v228
	v_lshlrev_b32_e32 v188, 5, v188
	v_lshl_add_u32 v188, s37, 2, v188
	global_load_dword v189, v188, s[42:43] offset:16
	global_load_dword v190, v188, s[42:43]
	v_mov_b32_e32 v188, s37
	v_or_b32_e32 v188, s35, v188
	v_lshlrev_b32_e32 v188, 2, v188
	global_load_dword v191, v188, s[98:99]
	global_load_dword v192, v188, s[100:101]
	s_add_u32 s98, s8, s16
	s_addc_u32 s99, s9, s17
	s_add_u32 s100, s8, s18
	s_addc_u32 s101, s9, s19
	s_add_u32 s30, s8, s22
	s_addc_u32 s31, s9, s23
	s_add_u32 s8, s8, s15
	s_addc_u32 s9, s9, s14
	global_load_dwordx4 v[34:37], v41, s[8:9] offset:48
	global_load_dwordx4 v[54:57], v41, s[8:9] offset:32
	global_load_dwordx4 v[58:61], v41, s[8:9] offset:16
	global_load_dwordx4 v[62:65], v41, s[8:9]
	global_load_dwordx4 v[140:143], v41, s[98:99] offset:48
	global_load_dwordx4 v[144:147], v41, s[98:99] offset:32
	global_load_dwordx4 v[148:151], v41, s[98:99] offset:16
	global_load_dwordx4 v[152:155], v41, s[98:99]
	global_load_dwordx4 v[156:159], v41, s[100:101] offset:48
	global_load_dwordx4 v[160:163], v41, s[100:101] offset:32
	global_load_dwordx4 v[164:167], v41, s[100:101] offset:16
	global_load_dwordx4 v[168:171], v41, s[100:101]
	global_load_dwordx4 v[172:175], v41, s[30:31] offset:48
	global_load_dwordx4 v[176:179], v41, s[30:31] offset:32
	global_load_dwordx4 v[180:183], v41, s[30:31] offset:16
	global_load_dwordx4 v[184:187], v41, s[30:31]
	v_lshl_add_u64 v[138:139], v[46:47], 0, v[16:17]
	v_lshl_add_u64 v[194:195], v[48:49], 0, v[16:17]
	v_lshl_add_u64 v[196:197], v[50:51], 0, v[16:17]
	v_lshl_add_u64 v[252:253], v[52:53], 0, v[16:17]
	global_load_dwordx4 v[208:211], v[138:139], off
	global_load_dwordx4 v[212:215], v[138:139], off offset:16
	global_load_dwordx4 v[216:219], v[194:195], off
	global_load_dwordx4 v[220:223], v[194:195], off offset:16
	global_load_dwordx4 v[224:227], v[196:197], off
	global_load_dwordx4 v[240:243], v[196:197], off offset:16
	global_load_dwordx4 v[244:247], v[252:253], off
	global_load_dwordx4 v[248:251], v[252:253], off offset:16
	s_mov_b32 s8, 0
	s_ashr_i32 s9, s8, 31
	s_lshl_b64 s[8:9], s[8:9], 3
	s_add_u32 s8, s0, s8
	s_addc_u32 s9, s1, s9
	v_lshl_add_u32 v110, v105, 6, v107
	s_waitcnt lgkmcnt(0)
	s_add_u32 s8, s8, s16
	s_addc_u32 s9, s9, s17
	s_waitcnt vmcnt(8)
	v_lshlrev_b32_e32 v43, 16, v30
	v_and_b32_e32 v30, 0xffff0000, v30
	v_lshlrev_b32_e32 v84, 16, v18
	v_and_b32_e32 v18, 0xffff0000, v18
	v_pk_mul_f32 v[58:59], v[44:45], v[58:59] op_sel_hi:[0,1]
	v_pk_mul_f32 v[62:63], v[44:45], v[62:63] op_sel_hi:[0,1]
	v_pk_mul_f32 v[64:65], v[44:45], v[64:65] op_sel_hi:[0,1]
	v_fma_f32 v82, v63, v30, 0
	v_lshlrev_b32_e32 v30, 16, v31
	v_fma_f32 v83, v62, v43, 0
	v_fma_f32 v81, v64, v30, 0
	v_and_b32_e32 v30, 0xffff0000, v31
	v_lshlrev_b32_e32 v43, 16, v32
	v_and_b32_e32 v32, 0xffff0000, v32
	v_fma_f32 v80, v65, v30, 0
	v_pk_mul_f32 v[30:31], v[44:45], v[60:61] op_sel_hi:[0,1]
	v_fma_f32 v78, v59, v32, 0
	v_lshlrev_b32_e32 v32, 16, v33
	v_fma_f32 v45, v30, v32, 0
	v_and_b32_e32 v30, 0xffff0000, v33
	v_fma_f32 v79, v58, v43, 0
	v_fma_f32 v43, v31, v30, 0
	v_pk_mul_f32 v[58:59], v[44:45], v[56:57] op_sel_hi:[0,1]
	v_pk_mul_f32 v[62:63], v[44:45], v[54:55] op_sel_hi:[0,1]
	v_pk_mul_f32 v[54:55], v[44:45], v[36:37] op_sel_hi:[0,1]
	v_pk_mul_f32 v[56:57], v[44:45], v[34:35] op_sel_hi:[0,1]
	v_mov_b64_e32 v[30:31], v[140:141]
	v_mov_b64_e32 v[32:33], v[142:143]
	v_mov_b64_e32 v[34:35], v[144:145]
	v_mov_b64_e32 v[36:37], v[146:147]
	v_mov_b64_e32 v[64:65], v[148:149]
	v_mov_b64_e32 v[66:67], v[150:151]
	v_mov_b64_e32 v[68:69], v[152:153]
	v_mov_b64_e32 v[70:71], v[154:155]
	s_mov_b32 s8, 0
	s_ashr_i32 s9, s8, 31
	s_lshl_b64 s[8:9], s[8:9], 3
	s_add_u32 s8, s0, s8
	s_addc_u32 s9, s1, s9
	s_waitcnt lgkmcnt(0)
	s_add_u32 s8, s8, s18
	s_addc_u32 s9, s9, s19
	s_waitcnt vmcnt(8)
	v_pk_mul_f32 v[60:61], v[42:43], v[70:71] op_sel_hi:[0,1]
	v_pk_mul_f32 v[68:69], v[42:43], v[68:69] op_sel_hi:[0,1]
	v_lshlrev_b32_e32 v70, 16, v26
	v_and_b32_e32 v26, 0xffff0000, v26
	v_fmac_f32_e32 v82, v69, v26
	v_lshlrev_b32_e32 v26, 16, v27
	v_fmac_f32_e32 v81, v60, v26
	v_and_b32_e32 v26, 0xffff0000, v27
	v_fmac_f32_e32 v80, v61, v26
	v_pk_mul_f32 v[60:61], v[42:43], v[64:65] op_sel_hi:[0,1]
	v_lshlrev_b32_e32 v64, 16, v28
	v_and_b32_e32 v28, 0xffff0000, v28
	v_pk_mul_f32 v[26:27], v[42:43], v[66:67] op_sel_hi:[0,1]
	v_fmac_f32_e32 v78, v61, v28
	v_lshlrev_b32_e32 v28, 16, v29
	v_fmac_f32_e32 v45, v26, v28
	v_and_b32_e32 v26, 0xffff0000, v29
	v_fmac_f32_e32 v43, v27, v26
	v_fmac_f32_e32 v83, v68, v70
	v_fmac_f32_e32 v79, v60, v64
	v_pk_mul_f32 v[66:67], v[42:43], v[36:37] op_sel_hi:[0,1]
	v_pk_mul_f32 v[70:71], v[42:43], v[34:35] op_sel_hi:[0,1]
	v_pk_mul_f32 v[60:61], v[42:43], v[32:33] op_sel_hi:[0,1]
	v_pk_mul_f32 v[64:65], v[42:43], v[30:31] op_sel_hi:[0,1]
	v_mov_b64_e32 v[26:27], v[156:157]
	v_mov_b64_e32 v[28:29], v[158:159]
	v_mov_b64_e32 v[30:31], v[160:161]
	v_mov_b64_e32 v[32:33], v[162:163]
	v_mov_b64_e32 v[34:35], v[164:165]
	v_mov_b64_e32 v[36:37], v[166:167]
	v_mov_b64_e32 v[72:73], v[168:169]
	v_mov_b64_e32 v[74:75], v[170:171]
	s_mov_b32 s8, 0
	s_ashr_i32 s9, s8, 31
	s_lshl_b64 s[8:9], s[8:9], 3
	s_add_u32 s8, s0, s8
	s_addc_u32 s9, s1, s9
	s_waitcnt lgkmcnt(0)
	s_add_u32 s8, s8, s22
	s_addc_u32 s9, s9, s23
	s_waitcnt vmcnt(10)
	v_pk_mul_f32 v[76:77], v[40:41], v[30:31] op_sel_hi:[0,1]
	s_waitcnt vmcnt(9)
	v_pk_mul_f32 v[34:35], v[40:41], v[34:35] op_sel_hi:[0,1]
	s_waitcnt vmcnt(8)
	v_pk_mul_f32 v[68:69], v[40:41], v[74:75] op_sel_hi:[0,1]
	v_pk_mul_f32 v[72:73], v[40:41], v[72:73] op_sel_hi:[0,1]
	v_lshlrev_b32_e32 v74, 16, v22
	v_and_b32_e32 v22, 0xffff0000, v22
	v_fmac_f32_e32 v82, v73, v22
	v_lshlrev_b32_e32 v22, 16, v23
	v_fmac_f32_e32 v81, v68, v22
	v_and_b32_e32 v22, 0xffff0000, v23
	v_fmac_f32_e32 v80, v69, v22
	v_pk_mul_f32 v[22:23], v[40:41], v[36:37] op_sel_hi:[0,1]
	v_lshlrev_b32_e32 v36, 16, v24
	v_and_b32_e32 v24, 0xffff0000, v24
	v_fmac_f32_e32 v78, v35, v24
	v_lshlrev_b32_e32 v24, 16, v25
	v_fmac_f32_e32 v45, v22, v24
	v_and_b32_e32 v22, 0xffff0000, v25
	v_fmac_f32_e32 v83, v72, v74
	v_fmac_f32_e32 v79, v34, v36
	v_fmac_f32_e32 v43, v23, v22
	v_pk_mul_f32 v[74:75], v[40:41], v[32:33] op_sel_hi:[0,1]
	v_pk_mul_f32 v[68:69], v[40:41], v[28:29] op_sel_hi:[0,1]
	v_pk_mul_f32 v[72:73], v[40:41], v[26:27] op_sel_hi:[0,1]
	v_mov_b64_e32 v[22:23], v[172:173]
	v_mov_b64_e32 v[24:25], v[174:175]
	v_mov_b64_e32 v[26:27], v[176:177]
	v_mov_b64_e32 v[28:29], v[178:179]
	v_mov_b64_e32 v[30:31], v[180:181]
	v_mov_b64_e32 v[32:33], v[182:183]
	v_mov_b64_e32 v[34:35], v[184:185]
	v_mov_b64_e32 v[36:37], v[186:187]
	s_waitcnt vmcnt(10)
	v_pk_mul_f32 v[26:27], v[38:39], v[26:27] op_sel_hi:[0,1]
	s_waitcnt vmcnt(9)
	v_pk_mul_f32 v[30:31], v[38:39], v[30:31] op_sel_hi:[0,1]
	s_waitcnt vmcnt(8)
	v_pk_mul_f32 v[34:35], v[38:39], v[34:35] op_sel_hi:[0,1]
	v_pk_mul_f32 v[36:37], v[38:39], v[36:37] op_sel_hi:[0,1]
	v_fmac_f32_e32 v82, v35, v18
	v_lshlrev_b32_e32 v18, 16, v19
	v_fmac_f32_e32 v81, v36, v18
	v_and_b32_e32 v18, 0xffff0000, v19
	v_fmac_f32_e32 v80, v37, v18
	v_pk_mul_f32 v[18:19], v[38:39], v[32:33] op_sel_hi:[0,1]
	v_lshlrev_b32_e32 v32, 16, v20
	v_and_b32_e32 v20, 0xffff0000, v20
	v_fmac_f32_e32 v83, v34, v84
	v_fmac_f32_e32 v78, v31, v20
	v_lshlrev_b32_e32 v20, 16, v21
	v_fmac_f32_e32 v45, v18, v20
	v_and_b32_e32 v18, 0xffff0000, v21
	v_pk_mul_f32 v[20:21], v[38:39], v[22:23] op_sel_hi:[0,1]
	v_mul_f32_e32 v22, 0xbfb8aa3b, v83
	v_exp_f32_e32 v22, v22
	v_fmac_f32_e32 v79, v30, v32
	v_fmac_f32_e32 v43, v19, v18
	v_and_b32_e32 v23, 0xffff0000, v0
	v_add_f32_e32 v22, 1.0, v22
	v_rcp_f32_e32 v22, v22
	v_pk_mul_f32 v[18:19], v[38:39], v[24:25] op_sel_hi:[0,1]
	v_and_b32_e32 v25, 0xffff0000, v4
	v_lshlrev_b32_e32 v24, 16, v4
	v_mul_f32_e32 v30, v83, v22
	v_mul_f32_e32 v22, 0xbfb8aa3b, v82
	v_exp_f32_e32 v22, v22
	v_lshlrev_b32_e32 v4, 16, v9
	v_pk_mul_f32 v[28:29], v[38:39], v[28:29] op_sel_hi:[0,1]
	v_add_f32_e32 v22, 1.0, v22
	v_rcp_f32_e32 v22, v22
	s_nop 0
	v_mul_f32_e32 v31, v82, v22
	v_mul_f32_e32 v22, 0xbfb8aa3b, v81
	v_exp_f32_e32 v22, v22
	s_nop 0
	v_add_f32_e32 v22, 1.0, v22
	v_rcp_f32_e32 v22, v22
	s_nop 0
	v_mul_f32_e32 v32, v81, v22
	v_mul_f32_e32 v22, 0xbfb8aa3b, v80
	v_exp_f32_e32 v22, v22
	s_nop 0
	v_add_f32_e32 v22, 1.0, v22
	v_rcp_f32_e32 v22, v22
	s_nop 0
	v_mul_f32_e32 v33, v80, v22
	v_mul_f32_e32 v22, 0xbfb8aa3b, v79
	v_exp_f32_e32 v22, v22
	s_nop 0
	v_add_f32_e32 v22, 1.0, v22
	v_rcp_f32_e32 v22, v22
	s_nop 0
	v_mul_f32_e32 v34, v79, v22
	v_mul_f32_e32 v22, 0xbfb8aa3b, v78
	v_exp_f32_e32 v22, v22
	s_nop 0
	v_add_f32_e32 v22, 1.0, v22
	v_rcp_f32_e32 v22, v22
	s_nop 0
	v_mul_f32_e32 v35, v78, v22
	v_mul_f32_e32 v22, 0xbfb8aa3b, v45
	v_exp_f32_e32 v22, v22
	s_nop 0
	v_add_f32_e32 v22, 1.0, v22
	v_rcp_f32_e32 v22, v22
	s_nop 0
	v_mul_f32_e32 v36, v45, v22
	v_mul_f32_e32 v22, 0xbfb8aa3b, v43
	v_exp_f32_e32 v22, v22
	s_nop 0
	v_add_f32_e32 v22, 1.0, v22
	v_rcp_f32_e32 v22, v22
	s_nop 0
	v_mul_f32_e32 v37, v43, v22
	v_lshlrev_b32_e32 v22, 16, v0
	v_pk_fma_f32 v[22:23], v[62:63], v[22:23], 0 op_sel_hi:[1,1,0]
	v_mul_f32_e32 v43, v31, v31
	v_pk_fma_f32 v[22:23], v[70:71], v[24:25], v[22:23]
	v_and_b32_e32 v25, 0xffff0000, v8
	v_lshlrev_b32_e32 v24, 16, v8
	v_pk_fma_f32 v[22:23], v[76:77], v[24:25], v[22:23]
	v_and_b32_e32 v25, 0xffff0000, v12
	v_lshlrev_b32_e32 v24, 16, v12
	v_pk_fma_f32 v[22:23], v[26:27], v[24:25], v[22:23]
	v_fmac_f32_e32 v43, v30, v30
	v_mul_f32_e32 v0, 0xbfb8aa3b, v22
	v_exp_f32_e32 v0, v0
	v_fmac_f32_e32 v43, v32, v32
	v_fmac_f32_e32 v43, v33, v33
	v_fmac_f32_e32 v43, v34, v34
	v_add_f32_e32 v0, 1.0, v0
	v_rcp_f32_e32 v24, v0
	v_mul_f32_e32 v0, 0xbfb8aa3b, v23
	v_exp_f32_e32 v0, v0
	v_fmac_f32_e32 v43, v35, v35
	v_fmac_f32_e32 v43, v36, v36
	v_fmac_f32_e32 v43, v37, v37
	v_add_f32_e32 v0, 1.0, v0
	v_rcp_f32_e32 v25, v0
	s_nop 0
	v_pk_mul_f32 v[22:23], v[22:23], v[24:25]
	s_nop 0
	v_pk_mul_f32 v[24:25], v[22:23], v[22:23]
	s_nop 0
	v_add_f32_e32 v0, v24, v43
	v_add_f32_e32 v8, v25, v0
	v_and_b32_e32 v25, 0xffff0000, v1
	v_lshlrev_b32_e32 v24, 16, v1
	v_pk_fma_f32 v[0:1], v[58:59], v[24:25], 0 op_sel_hi:[1,1,0]
	v_and_b32_e32 v25, 0xffff0000, v5
	v_lshlrev_b32_e32 v24, 16, v5
	v_pk_fma_f32 v[0:1], v[66:67], v[24:25], v[0:1]
	v_and_b32_e32 v5, 0xffff0000, v9
	v_pk_fma_f32 v[0:1], v[74:75], v[4:5], v[0:1]
	v_and_b32_e32 v5, 0xffff0000, v13
	v_lshlrev_b32_e32 v4, 16, v13
	v_pk_fma_f32 v[0:1], v[28:29], v[4:5], v[0:1]
	v_and_b32_e32 v9, 0xffff0000, v6
	v_mul_f32_e32 v4, 0xbfb8aa3b, v0
	v_mul_f32_e32 v5, 0xbfb8aa3b, v1
	v_exp_f32_e32 v4, v4
	v_exp_f32_e32 v5, v5
	v_add_f32_e32 v4, 1.0, v4
	v_add_f32_e32 v5, 1.0, v5
	v_rcp_f32_e32 v4, v4
	v_rcp_f32_e32 v5, v5
	s_nop 0
	v_pk_mul_f32 v[0:1], v[0:1], v[4:5]
	s_nop 0
	v_pk_mul_f32 v[4:5], v[0:1], v[0:1]
	s_nop 0
	v_add_f32_e32 v4, v4, v8
	v_add_f32_e32 v12, v5, v4
	v_and_b32_e32 v5, 0xffff0000, v2
	v_lshlrev_b32_e32 v4, 16, v2
	v_pk_fma_f32 v[4:5], v[56:57], v[4:5], 0 op_sel_hi:[1,1,0]
	v_lshlrev_b32_e32 v8, 16, v6
	v_pk_fma_f32 v[4:5], v[64:65], v[8:9], v[4:5]
	v_and_b32_e32 v9, 0xffff0000, v10
	v_lshlrev_b32_e32 v8, 16, v10
	v_pk_fma_f32 v[4:5], v[72:73], v[8:9], v[4:5]
	v_and_b32_e32 v9, 0xffff0000, v14
	v_lshlrev_b32_e32 v8, 16, v14
	v_pk_fma_f32 v[4:5], v[20:21], v[8:9], v[4:5]
	v_lshlrev_b32_e32 v6, 16, v11
	v_mul_f32_e32 v2, 0xbfb8aa3b, v4
	v_exp_f32_e32 v2, v2
	s_nop 0
	v_add_f32_e32 v2, 1.0, v2
	v_rcp_f32_e32 v8, v2
	v_mul_f32_e32 v2, 0xbfb8aa3b, v5
	v_exp_f32_e32 v2, v2
	s_nop 0
	v_add_f32_e32 v2, 1.0, v2
	v_rcp_f32_e32 v9, v2
	s_nop 0
	v_pk_mul_f32 v[4:5], v[4:5], v[8:9]
	s_nop 0
	v_pk_mul_f32 v[8:9], v[4:5], v[4:5]
	s_nop 0
	v_add_f32_e32 v2, v8, v12
	v_add_f32_e32 v10, v9, v2
	v_and_b32_e32 v9, 0xffff0000, v3
	v_lshlrev_b32_e32 v8, 16, v3
	v_pk_fma_f32 v[2:3], v[54:55], v[8:9], 0 op_sel_hi:[1,1,0]
	v_and_b32_e32 v9, 0xffff0000, v7
	v_lshlrev_b32_e32 v8, 16, v7
	v_pk_fma_f32 v[2:3], v[60:61], v[8:9], v[2:3]
	v_and_b32_e32 v7, 0xffff0000, v11
	v_pk_fma_f32 v[2:3], v[68:69], v[6:7], v[2:3]
	v_and_b32_e32 v7, 0xffff0000, v15
	v_lshlrev_b32_e32 v6, 16, v15
	v_pk_fma_f32 v[2:3], v[18:19], v[6:7], v[2:3]
	v_add_u32_e32 v8, 64, v111
	v_mul_f32_e32 v6, 0xbfb8aa3b, v3
	v_exp_f32_e32 v6, v6
	s_nop 0
	v_add_f32_e32 v6, 1.0, v6
	v_rcp_f32_e32 v7, v6
	v_mul_f32_e32 v6, 0xbfb8aa3b, v2
	v_exp_f32_e32 v6, v6
	s_nop 0
	v_add_f32_e32 v6, 1.0, v6
	v_rcp_f32_e32 v6, v6
	s_nop 0
	v_pk_mul_f32 v[2:3], v[2:3], v[6:7]
	s_nop 0
	v_pk_mul_f32 v[6:7], v[2:3], v[2:3]
	s_nop 0
	v_add_f32_e32 v6, v6, v10
	v_add_f32_e32 v6, v7, v6
	v_xor_b32_e32 v7, 1, v234
	v_cmp_lt_i32_e32 vcc, v7, v8
	s_nop 1
	v_cndmask_b32_e32 v7, v234, v7, vcc
	v_lshlrev_b32_e32 v45, 2, v7
	ds_bpermute_b32 v7, v45, v6
	s_waitcnt lgkmcnt(0)
	v_add_f32_e32 v6, v6, v7
	v_xor_b32_e32 v7, 2, v234
	v_cmp_lt_i32_e32 vcc, v7, v8
	s_nop 1
	v_cndmask_b32_e32 v7, v234, v7, vcc
	v_lshlrev_b32_e32 v112, 2, v7
	ds_bpermute_b32 v7, v112, v6
	s_waitcnt lgkmcnt(0)
	v_add_f32_e32 v6, v6, v7
	v_xor_b32_e32 v7, 4, v234
	v_cmp_lt_i32_e32 vcc, v7, v8
	s_nop 1
	v_cndmask_b32_e32 v7, v234, v7, vcc
	v_lshlrev_b32_e32 v113, 2, v7
	ds_bpermute_b32 v7, v113, v6
	s_waitcnt lgkmcnt(0)
	v_add_f32_e32 v6, v6, v7
	v_add_f32_e32 v6, 0x358637bd, v6
	v_cmp_gt_f32_e32 vcc, s33, v6
	v_mul_f32_e32 v7, 0x4b800000, v6
	s_nop 0
	v_cndmask_b32_e32 v6, v6, v7, vcc
	v_rsq_f32_e32 v6, v6
	s_nop 0
	v_mul_f32_e32 v7, 0x45800000, v6
	v_cndmask_b32_e32 v6, v6, v7, vcc
	v_mul_f32_e32 v6, 0x3db504f3, v6
	v_mul_f32_e32 v7, v30, v6
	v_mul_f32_e32 v8, v31, v6
	v_mul_f32_e32 v9, v32, v6
	v_mul_f32_e32 v10, v33, v6
	v_mul_f32_e32 v11, v34, v6
	v_mul_f32_e32 v12, v35, v6
	v_mul_f32_e32 v13, v36, v6
	v_mul_f32_e32 v14, v37, v6
	v_mul_f32_e32 v15, v22, v6
	v_mul_f32_e32 v18, v23, v6
	v_mul_f32_e32 v0, v0, v6
	v_mul_f32_e32 v1, v1, v6
	v_mul_f32_e32 v4, v4, v6
	v_mul_f32_e32 v5, v5, v6
	v_mul_f32_e32 v2, v2, v6
	v_mul_f32_e32 v3, v3, v6
	v_lshlrev_b32_e32 v6, 5, v105
	v_add3_u32 v43, 0, v6, v109
	v_cvt_pk_bf16_f32 v6, v7, v8
	v_add_u32_e32 v8, 0x4400, v43
	v_cvt_pk_bf16_f32 v7, v9, v10
	ds_write2_b32 v8, v6, v7 offset1:1
	v_cvt_pk_bf16_f32 v6, v11, v12
	v_cvt_pk_bf16_f32 v0, v0, v1
	v_cvt_pk_bf16_f32 v7, v13, v14
	ds_write2_b32 v8, v6, v7 offset0:2 offset1:3
	v_cvt_pk_bf16_f32 v6, v15, v18
	ds_write2_b32 v8, v6, v0 offset0:4 offset1:5
	v_cvt_pk_bf16_f32 v0, v4, v5
	v_cvt_pk_bf16_f32 v1, v2, v3
	ds_write2_b32 v8, v0, v1 offset0:6 offset1:7
	s_waitcnt vmcnt(0)
	s_nop 1
	v_mov_b64_e32 v[30:31], v[208:209]
	v_mov_b64_e32 v[32:33], v[210:211]
	v_mov_b64_e32 v[12:13], v[212:213]
	v_mov_b64_e32 v[14:15], v[214:215]
	v_mov_b64_e32 v[26:27], v[216:217]
	v_mov_b64_e32 v[28:29], v[218:219]
	v_mov_b64_e32 v[8:9], v[220:221]
	v_mov_b64_e32 v[10:11], v[222:223]
	v_mov_b64_e32 v[22:23], v[224:225]
	v_mov_b64_e32 v[24:25], v[226:227]
	v_mov_b64_e32 v[4:5], v[240:241]
	v_mov_b64_e32 v[6:7], v[242:243]
	v_mov_b64_e32 v[18:19], v[244:245]
	v_mov_b64_e32 v[20:21], v[246:247]
	v_mov_b64_e32 v[0:1], v[248:249]
	v_mov_b64_e32 v[2:3], v[250:251]
	s_mov_b32 s8, 0
	s_ashr_i32 s9, s8, 31
	s_lshl_b64 s[8:9], s[8:9], 3
	s_add_u32 s8, s0, s8
	s_addc_u32 s9, s1, s9
	s_load_dwordx2 s[8:9], s[8:9], 0x90
	s_waitcnt lgkmcnt(0)
	s_add_u32 s98, s8, s16
	s_addc_u32 s99, s9, s17
	s_add_u32 s100, s8, s18
	s_addc_u32 s101, s9, s19
	s_add_u32 s30, s8, s22
	s_addc_u32 s31, s9, s23
	s_add_u32 s8, s8, s15
	s_addc_u32 s9, s9, s14
	global_load_dwordx4 v[58:61], v41, s[8:9] offset:2096
	global_load_dwordx4 v[62:65], v41, s[8:9] offset:2080
	global_load_dwordx4 v[34:37], v41, s[8:9] offset:2064
	global_load_dwordx4 v[54:57], v41, s[8:9] offset:2048
	global_load_dwordx4 v[140:143], v41, s[98:99] offset:2096
	global_load_dwordx4 v[144:147], v41, s[98:99] offset:2080
	global_load_dwordx4 v[148:151], v41, s[98:99] offset:2064
	global_load_dwordx4 v[152:155], v41, s[98:99] offset:2048
	global_load_dwordx4 v[156:159], v41, s[100:101] offset:2096
	global_load_dwordx4 v[160:163], v41, s[100:101] offset:2080
	global_load_dwordx4 v[164:167], v41, s[100:101] offset:2064
	global_load_dwordx4 v[168:171], v41, s[100:101] offset:2048
	global_load_dwordx4 v[172:175], v41, s[30:31] offset:2096
	global_load_dwordx4 v[176:179], v41, s[30:31] offset:2080
	global_load_dwordx4 v[180:183], v41, s[30:31] offset:2064
	global_load_dwordx4 v[184:187], v41, s[30:31] offset:2048
	global_load_dwordx4 v[208:211], v[138:139], off offset:1024
	global_load_dwordx4 v[212:215], v[138:139], off offset:1040
	global_load_dwordx4 v[216:219], v[194:195], off offset:1024
	global_load_dwordx4 v[220:223], v[194:195], off offset:1040
	global_load_dwordx4 v[224:227], v[196:197], off offset:1024
	global_load_dwordx4 v[240:243], v[196:197], off offset:1040
	global_load_dwordx4 v[244:247], v[252:253], off offset:1024
	global_load_dwordx4 v[248:251], v[252:253], off offset:1040
	s_mov_b32 s8, 0
	s_ashr_i32 s9, s8, 31
	s_lshl_b64 s[8:9], s[8:9], 3
	s_add_u32 s8, s0, s8
	s_addc_u32 s9, s1, s9
	s_waitcnt lgkmcnt(0)
	s_add_u32 s8, s8, s16
	s_addc_u32 s9, s9, s17
	s_waitcnt vmcnt(8)
	v_pk_mul_f32 v[92:93], v[44:45], v[60:61] op_sel_hi:[0,1]
	v_pk_mul_f32 v[74:75], v[44:45], v[58:59] op_sel_hi:[0,1]
	v_pk_mul_f32 v[66:67], v[44:45], v[34:35] op_sel_hi:[0,1]
	v_pk_mul_f32 v[78:79], v[44:45], v[54:55] op_sel_hi:[0,1]
	v_pk_mul_f32 v[34:35], v[44:45], v[64:65] op_sel_hi:[0,1]
	v_pk_mul_f32 v[54:55], v[44:45], v[62:63] op_sel_hi:[0,1]
	v_mov_b64_e32 v[82:83], v[140:141]
	v_mov_b64_e32 v[84:85], v[142:143]
	v_mov_b64_e32 v[58:59], v[144:145]
	v_mov_b64_e32 v[60:61], v[146:147]
	v_mov_b64_e32 v[88:89], v[148:149]
	v_mov_b64_e32 v[90:91], v[150:151]
	v_mov_b64_e32 v[62:63], v[152:153]
	v_mov_b64_e32 v[64:65], v[154:155]
	s_mov_b32 s8, 0
	s_ashr_i32 s9, s8, 31
	s_lshl_b64 s[8:9], s[8:9], 3
	s_add_u32 s8, s0, s8
	s_addc_u32 s9, s1, s9
	v_pk_mul_f32 v[70:71], v[44:45], v[56:57] op_sel_hi:[0,1]
	v_pk_mul_f32 v[56:57], v[44:45], v[36:37] op_sel_hi:[0,1]
	s_waitcnt lgkmcnt(0)
	s_add_u32 s8, s8, s18
	s_addc_u32 s9, s9, s19
	v_mov_b64_e32 v[100:101], v[156:157]
	v_mov_b64_e32 v[102:103], v[158:159]
	v_mov_b64_e32 v[114:115], v[160:161]
	v_mov_b64_e32 v[116:117], v[162:163]
	v_mov_b64_e32 v[118:119], v[164:165]
	v_mov_b64_e32 v[120:121], v[166:167]
	v_mov_b64_e32 v[94:95], v[168:169]
	v_mov_b64_e32 v[96:97], v[170:171]
	s_mov_b32 s8, 0
	s_ashr_i32 s9, s8, 31
	s_lshl_b64 s[8:9], s[8:9], 3
	s_add_u32 s8, s0, s8
	s_addc_u32 s9, s1, s9
	s_waitcnt lgkmcnt(0)
	s_add_u32 s8, s8, s22
	s_addc_u32 s9, s9, s23
	s_waitcnt vmcnt(15)
	v_pk_mul_f32 v[98:99], v[42:43], v[84:85] op_sel_hi:[0,1]
	s_waitcnt vmcnt(14)
	v_pk_mul_f32 v[36:37], v[42:43], v[60:61] op_sel_hi:[0,1]
	v_pk_mul_f32 v[60:61], v[42:43], v[58:59] op_sel_hi:[0,1]
	s_waitcnt vmcnt(12)
	v_pk_mul_f32 v[80:81], v[42:43], v[64:65] op_sel_hi:[0,1]
	v_pk_mul_f32 v[84:85], v[42:43], v[82:83] op_sel_hi:[0,1]
	v_pk_mul_f32 v[86:87], v[42:43], v[62:63] op_sel_hi:[0,1]
	v_pk_mul_f32 v[62:63], v[42:43], v[90:91] op_sel_hi:[0,1]
	v_pk_mul_f32 v[72:73], v[42:43], v[88:89] op_sel_hi:[0,1]
	s_waitcnt vmcnt(11)
	v_pk_mul_f32 v[130:131], v[40:41], v[100:101] op_sel_hi:[0,1]
	s_waitcnt vmcnt(10)
	v_pk_mul_f32 v[58:59], v[40:41], v[116:117] op_sel_hi:[0,1]
	s_waitcnt vmcnt(9)
	v_pk_mul_f32 v[68:69], v[40:41], v[120:121] op_sel_hi:[0,1]
	v_pk_mul_f32 v[82:83], v[40:41], v[118:119] op_sel_hi:[0,1]
	v_pk_mul_f32 v[64:65], v[40:41], v[114:115] op_sel_hi:[0,1]
	v_mov_b64_e32 v[114:115], v[172:173]
	v_mov_b64_e32 v[116:117], v[174:175]
	v_mov_b64_e32 v[118:119], v[176:177]
	v_mov_b64_e32 v[120:121], v[178:179]
	v_mov_b64_e32 v[122:123], v[180:181]
	v_mov_b64_e32 v[124:125], v[182:183]
	v_mov_b64_e32 v[126:127], v[184:185]
	v_mov_b64_e32 v[128:129], v[186:187]
	v_pk_mul_f32 v[102:103], v[40:41], v[102:103] op_sel_hi:[0,1]
	s_waitcnt vmcnt(12)
	v_pk_mul_f32 v[88:89], v[40:41], v[96:97] op_sel_hi:[0,1]
	v_pk_mul_f32 v[96:97], v[40:41], v[94:95] op_sel_hi:[0,1]
	s_waitcnt vmcnt(11)
	v_pk_mul_f32 v[114:115], v[38:39], v[114:115] op_sel_hi:[0,1]
	s_waitcnt vmcnt(10)
	v_pk_mul_f32 v[90:91], v[38:39], v[118:119] op_sel_hi:[0,1]
	v_and_b32_e32 v119, 0xffff0000, v14
	v_lshlrev_b32_e32 v118, 16, v14
	v_pk_fma_f32 v[74:75], v[74:75], v[118:119], 0 op_sel_hi:[1,1,0]
	v_and_b32_e32 v119, 0xffff0000, v10
	v_lshlrev_b32_e32 v118, 16, v10
	v_pk_fma_f32 v[74:75], v[84:85], v[118:119], v[74:75]
	v_and_b32_e32 v85, 0xffff0000, v6
	v_lshlrev_b32_e32 v84, 16, v6
	v_pk_fma_f32 v[74:75], v[130:131], v[84:85], v[74:75]
	v_and_b32_e32 v85, 0xffff0000, v2
	v_lshlrev_b32_e32 v84, 16, v2
	v_pk_fma_f32 v[74:75], v[114:115], v[84:85], v[74:75]
	v_and_b32_e32 v115, 0xffff0000, v15
	v_mul_f32_e32 v2, 0xbfb8aa3b, v74
	v_exp_f32_e32 v2, v2
	v_lshlrev_b32_e32 v114, 16, v15
	v_pk_fma_f32 v[14:15], v[92:93], v[114:115], 0 op_sel_hi:[1,1,0]
	v_and_b32_e32 v93, 0xffff0000, v11
	v_add_f32_e32 v2, 1.0, v2
	v_rcp_f32_e32 v84, v2
	v_mul_f32_e32 v2, 0xbfb8aa3b, v75
	v_exp_f32_e32 v2, v2
	v_lshlrev_b32_e32 v92, 16, v11
	v_pk_fma_f32 v[10:11], v[98:99], v[92:93], v[14:15]
	v_and_b32_e32 v15, 0xffff0000, v7
	v_lshlrev_b32_e32 v14, 16, v7
	v_pk_mul_f32 v[116:117], v[38:39], v[116:117] op_sel_hi:[0,1]
	v_add_f32_e32 v2, 1.0, v2
	v_pk_fma_f32 v[6:7], v[102:103], v[14:15], v[10:11]
	v_and_b32_e32 v11, 0xffff0000, v3
	v_lshlrev_b32_e32 v10, 16, v3
	v_rcp_f32_e32 v85, v2
	v_pk_fma_f32 v[2:3], v[116:117], v[10:11], v[6:7]
	v_lshlrev_b32_e32 v10, 16, v30
	v_and_b32_e32 v11, 0xffff0000, v30
	v_lshlrev_b32_e32 v30, 16, v31
	v_and_b32_e32 v31, 0xffff0000, v31
	v_pk_fma_f32 v[10:11], v[78:79], v[10:11], 0 op_sel_hi:[1,1,0]
	v_lshlrev_b32_e32 v14, 16, v26
	v_and_b32_e32 v15, 0xffff0000, v26
	v_pk_fma_f32 v[30:31], v[70:71], v[30:31], 0 op_sel_hi:[1,1,0]
	v_lshlrev_b32_e32 v26, 16, v27
	v_and_b32_e32 v27, 0xffff0000, v27
	v_pk_fma_f32 v[10:11], v[86:87], v[14:15], v[10:11]
	v_lshlrev_b32_e32 v14, 16, v22
	v_and_b32_e32 v15, 0xffff0000, v22
	v_pk_fma_f32 v[26:27], v[80:81], v[26:27], v[30:31]
	v_lshlrev_b32_e32 v22, 16, v23
	v_and_b32_e32 v23, 0xffff0000, v23
	s_waitcnt vmcnt(8)
	v_pk_mul_f32 v[128:129], v[38:39], v[128:129] op_sel_hi:[0,1]
	v_pk_fma_f32 v[10:11], v[96:97], v[14:15], v[10:11]
	v_lshlrev_b32_e32 v14, 16, v18
	v_and_b32_e32 v15, 0xffff0000, v18
	v_pk_fma_f32 v[22:23], v[88:89], v[22:23], v[26:27]
	v_lshlrev_b32_e32 v18, 16, v19
	v_and_b32_e32 v19, 0xffff0000, v19
	v_pk_fma_f32 v[18:19], v[128:129], v[18:19], v[22:23]
	v_lshlrev_b32_e32 v26, 16, v32
	v_mul_f32_e32 v16, 0xbfb8aa3b, v18
	v_exp_f32_e32 v16, v16
	v_and_b32_e32 v27, 0xffff0000, v32
	v_pk_fma_f32 v[26:27], v[66:67], v[26:27], 0 op_sel_hi:[1,1,0]
	v_lshlrev_b32_e32 v30, 16, v28
	v_add_f32_e32 v16, 1.0, v16
	v_rcp_f32_e32 v22, v16
	v_mul_f32_e32 v16, 0xbfb8aa3b, v19
	v_exp_f32_e32 v16, v16
	v_and_b32_e32 v31, 0xffff0000, v28
	v_pk_fma_f32 v[26:27], v[72:73], v[30:31], v[26:27]
	v_lshlrev_b32_e32 v30, 16, v24
	v_and_b32_e32 v31, 0xffff0000, v24
	v_pk_mul_f32 v[100:101], v[38:39], v[122:123] op_sel_hi:[0,1]
	v_pk_fma_f32 v[26:27], v[82:83], v[30:31], v[26:27]
	v_lshlrev_b32_e32 v30, 16, v20
	v_and_b32_e32 v31, 0xffff0000, v20
	v_add_f32_e32 v16, 1.0, v16
	v_pk_fma_f32 v[26:27], v[100:101], v[30:31], v[26:27]
	v_rcp_f32_e32 v23, v16
	v_mul_f32_e32 v16, 0xbfb8aa3b, v26
	v_lshlrev_b32_e32 v32, 16, v33
	v_and_b32_e32 v33, 0xffff0000, v33
	v_exp_f32_e32 v16, v16
	v_pk_fma_f32 v[32:33], v[56:57], v[32:33], 0 op_sel_hi:[1,1,0]
	v_lshlrev_b32_e32 v28, 16, v29
	v_and_b32_e32 v29, 0xffff0000, v29
	v_pk_fma_f32 v[28:29], v[62:63], v[28:29], v[32:33]
	v_lshlrev_b32_e32 v24, 16, v25
	v_and_b32_e32 v25, 0xffff0000, v25
	v_pk_fma_f32 v[24:25], v[68:69], v[24:25], v[28:29]
	v_lshlrev_b32_e32 v28, 16, v12
	v_and_b32_e32 v29, 0xffff0000, v12
	v_pk_fma_f32 v[28:29], v[54:55], v[28:29], 0 op_sel_hi:[1,1,0]
	v_lshlrev_b32_e32 v32, 16, v8
	v_and_b32_e32 v33, 0xffff0000, v8
	v_add_f32_e32 v16, 1.0, v16
	v_pk_fma_f32 v[28:29], v[60:61], v[32:33], v[28:29]
	v_lshlrev_b32_e32 v32, 16, v4
	v_and_b32_e32 v33, 0xffff0000, v4
	v_rcp_f32_e32 v30, v16
	v_mul_f32_e32 v16, 0xbfb8aa3b, v27
	v_pk_fma_f32 v[28:29], v[64:65], v[32:33], v[28:29]
	v_lshlrev_b32_e32 v32, 16, v0
	v_and_b32_e32 v33, 0xffff0000, v0
	v_exp_f32_e32 v16, v16
	v_pk_fma_f32 v[28:29], v[90:91], v[32:33], v[28:29]
	v_pk_mul_f32 v[94:95], v[38:39], v[124:125] op_sel_hi:[0,1]
	v_mul_f32_e32 v0, 0xbfb8aa3b, v28
	v_exp_f32_e32 v0, v0
	v_lshlrev_b32_e32 v20, 16, v21
	v_and_b32_e32 v21, 0xffff0000, v21
	v_pk_mul_f32 v[126:127], v[38:39], v[126:127] op_sel_hi:[0,1]
	v_add_f32_e32 v16, 1.0, v16
	v_pk_fma_f32 v[20:21], v[94:95], v[20:21], v[24:25]
	v_pk_fma_f32 v[10:11], v[126:127], v[14:15], v[10:11]
	v_rcp_f32_e32 v31, v16
	v_mul_f32_e32 v16, 0xbfb8aa3b, v20
	v_mul_f32_e32 v14, 0xbfb8aa3b, v10
	v_mul_f32_e32 v15, 0xbfb8aa3b, v11
	v_exp_f32_e32 v16, v16
	v_add_f32_e32 v0, 1.0, v0
	v_exp_f32_e32 v14, v14
	v_exp_f32_e32 v15, v15
	v_rcp_f32_e32 v32, v0
	v_mul_f32_e32 v0, 0xbfb8aa3b, v29
	v_exp_f32_e32 v0, v0
	v_add_f32_e32 v16, 1.0, v16
	v_lshlrev_b32_e32 v12, 16, v13
	v_and_b32_e32 v13, 0xffff0000, v13
	v_add_f32_e32 v14, 1.0, v14
	v_add_f32_e32 v15, 1.0, v15
	v_rcp_f32_e32 v24, v16
	v_mul_f32_e32 v16, 0xbfb8aa3b, v21
	v_pk_fma_f32 v[12:13], v[34:35], v[12:13], 0 op_sel_hi:[1,1,0]
	v_lshlrev_b32_e32 v8, 16, v9
	v_and_b32_e32 v9, 0xffff0000, v9
	v_rcp_f32_e32 v14, v14
	v_rcp_f32_e32 v15, v15
	v_exp_f32_e32 v16, v16
	v_add_f32_e32 v0, 1.0, v0
	v_pk_fma_f32 v[8:9], v[36:37], v[8:9], v[12:13]
	v_lshlrev_b32_e32 v4, 16, v5
	v_and_b32_e32 v5, 0xffff0000, v5
	v_pk_mul_f32 v[76:77], v[38:39], v[120:121] op_sel_hi:[0,1]
	v_mul_f32_e32 v6, 0xbfb8aa3b, v3
	v_rcp_f32_e32 v33, v0
	v_pk_fma_f32 v[4:5], v[58:59], v[4:5], v[8:9]
	v_lshlrev_b32_e32 v0, 16, v1
	v_and_b32_e32 v1, 0xffff0000, v1
	v_exp_f32_e32 v6, v6
	v_pk_fma_f32 v[0:1], v[76:77], v[0:1], v[4:5]
	v_pk_mul_f32 v[10:11], v[10:11], v[14:15]
	v_mul_f32_e32 v4, 0xbfb8aa3b, v0
	v_mul_f32_e32 v5, 0xbfb8aa3b, v1
	v_add_f32_e32 v16, 1.0, v16
	v_exp_f32_e32 v4, v4
	v_exp_f32_e32 v5, v5
	v_pk_mul_f32 v[14:15], v[10:11], v[10:11]
	v_pk_mul_f32 v[18:19], v[18:19], v[22:23]
	v_rcp_f32_e32 v25, v16
	v_add_f32_e32 v6, 1.0, v6
	v_pk_mul_f32 v[22:23], v[18:19], v[18:19]
	v_add_f32_e32 v8, v14, v15
	v_rcp_f32_e32 v7, v6
	v_mul_f32_e32 v6, 0xbfb8aa3b, v2
	v_pk_mul_f32 v[26:27], v[26:27], v[30:31]
	v_add_f32_e32 v8, v22, v8
	v_exp_f32_e32 v6, v6
	v_pk_mul_f32 v[30:31], v[26:27], v[26:27]
	v_add_f32_e32 v4, 1.0, v4
	v_add_f32_e32 v5, 1.0, v5
	v_add_f32_e32 v8, v23, v8
	v_pk_mul_f32 v[20:21], v[20:21], v[24:25]
	v_rcp_f32_e32 v4, v4
	v_rcp_f32_e32 v5, v5
	v_add_f32_e32 v8, v30, v8
	v_pk_mul_f32 v[24:25], v[20:21], v[20:21]
	v_add_f32_e32 v8, v31, v8
	v_pk_mul_f32 v[28:29], v[28:29], v[32:33]
	v_add_f32_e32 v8, v24, v8
	v_add_f32_e32 v6, 1.0, v6
	v_pk_mul_f32 v[32:33], v[28:29], v[28:29]
	v_add_f32_e32 v8, v25, v8
	v_rcp_f32_e32 v6, v6
	v_pk_mul_f32 v[0:1], v[0:1], v[4:5]
	v_add_f32_e32 v8, v32, v8
	v_pk_mul_f32 v[4:5], v[0:1], v[0:1]
	v_add_f32_e32 v8, v33, v8
	v_pk_mul_f32 v[74:75], v[74:75], v[84:85]
	v_add_f32_e32 v4, v4, v8
	v_pk_mul_f32 v[84:85], v[74:75], v[74:75]
	v_add_f32_e32 v4, v5, v4
	v_pk_mul_f32 v[2:3], v[2:3], v[6:7]
	v_add_f32_e32 v4, v84, v4
	v_pk_mul_f32 v[6:7], v[2:3], v[2:3]
	v_add_f32_e32 v4, v85, v4
	v_add_f32_e32 v4, v6, v4
	v_add_f32_e32 v4, v7, v4
	ds_bpermute_b32 v5, v45, v4
	v_or_b32_e32 v34, 0x400, v39
	s_waitcnt lgkmcnt(0)
	v_add_f32_e32 v4, v4, v5
	ds_bpermute_b32 v5, v112, v4
	s_waitcnt lgkmcnt(0)
	v_add_f32_e32 v4, v4, v5
	ds_bpermute_b32 v5, v113, v4
	s_waitcnt lgkmcnt(0)
	v_add_f32_e32 v4, v4, v5
	v_add_f32_e32 v4, 0x358637bd, v4
	v_cmp_gt_f32_e32 vcc, s33, v4
	v_mul_f32_e32 v5, 0x4b800000, v4
	s_nop 0
	v_cndmask_b32_e32 v4, v4, v5, vcc
	v_rsq_f32_e32 v4, v4
	s_nop 0
	v_mul_f32_e32 v5, 0x45800000, v4
	v_cndmask_b32_e32 v16, v4, v5, vcc
	v_pk_mul_f32 v[4:5], v[10:11], v[16:17] op_sel_hi:[1,0]
	v_pk_mul_f32 v[6:7], v[18:19], v[16:17] op_sel_hi:[1,0]
	v_pk_mul_f32 v[8:9], v[26:27], v[16:17] op_sel_hi:[1,0]
	v_pk_mul_f32 v[10:11], v[20:21], v[16:17] op_sel_hi:[1,0]
	v_pk_mul_f32 v[12:13], v[28:29], v[16:17] op_sel_hi:[1,0]
	v_pk_mul_f32 v[14:15], v[0:1], v[16:17] op_sel_hi:[1,0]
	v_pk_mul_f32 v[0:1], v[74:75], v[16:17] op_sel_hi:[1,0]
	v_pk_mul_f32 v[2:3], v[2:3], v[16:17] op_sel_hi:[1,0]
	v_cvt_pk_bf16_f32 v16, v4, v5
	v_cvt_pk_bf16_f32 v18, v6, v7
	ds_write2_b32 v43, v16, v18 offset1:1
	v_cvt_pk_bf16_f32 v16, v8, v9
	v_cvt_pk_bf16_f32 v18, v10, v11
	ds_write2_b32 v43, v16, v18 offset0:2 offset1:3
	v_cvt_pk_bf16_f32 v16, v12, v13
	v_cvt_pk_bf16_f32 v18, v14, v15
	ds_write2_b32 v43, v16, v18 offset0:4 offset1:5
	v_cvt_pk_bf16_f32 v16, v0, v1
	v_cvt_pk_bf16_f32 v18, v2, v3
	ds_write2_b32 v43, v16, v18 offset0:6 offset1:7
	ds_write_b128 v110, v[4:7] offset:35328
	ds_write_b128 v110, v[8:11] offset:35344
	ds_write_b128 v110, v[12:15] offset:35360
	ds_write_b128 v110, v[0:3] offset:35376
	s_waitcnt vmcnt(0)
	s_nop 1
	v_mov_b64_e32 v[12:13], v[208:209]
	v_mov_b64_e32 v[14:15], v[210:211]
	v_mov_b64_e32 v[30:31], v[212:213]
	v_mov_b64_e32 v[32:33], v[214:215]
	v_mov_b64_e32 v[8:9], v[216:217]
	v_mov_b64_e32 v[10:11], v[218:219]
	v_mov_b64_e32 v[26:27], v[220:221]
	v_mov_b64_e32 v[28:29], v[222:223]
	v_mov_b64_e32 v[4:5], v[224:225]
	v_mov_b64_e32 v[6:7], v[226:227]
	v_mov_b64_e32 v[22:23], v[240:241]
	v_mov_b64_e32 v[24:25], v[242:243]
	v_mov_b64_e32 v[0:1], v[244:245]
	v_mov_b64_e32 v[2:3], v[246:247]
	v_mov_b64_e32 v[18:19], v[248:249]
	v_mov_b64_e32 v[20:21], v[250:251]
	s_mov_b32 s8, 0
	s_ashr_i32 s9, s8, 31
	s_lshl_b64 s[8:9], s[8:9], 3
	s_add_u32 s8, s0, s8
	s_addc_u32 s9, s1, s9
	s_load_dwordx2 s[8:9], s[8:9], 0x90
	v_lshlrev_b32_e32 v16, 2, v34
	v_cmp_gt_u32_e32 vcc, 64, v106
	s_waitcnt lgkmcnt(0)
	s_add_u32 s98, s8, s16
	s_addc_u32 s99, s9, s17
	s_add_u32 s100, s8, s18
	s_addc_u32 s101, s9, s19
	s_add_u32 s30, s8, s22
	s_addc_u32 s31, s9, s23
	s_add_u32 s8, s8, s15
	s_addc_u32 s9, s9, s14
	global_load_dwordx4 v[52:55], v16, s[8:9] offset:48
	global_load_dwordx4 v[56:59], v16, s[8:9] offset:32
	global_load_dwordx4 v[48:51], v16, s[8:9] offset:16
	global_load_dwordx4 v[34:37], v16, s[8:9]
	global_load_dwordx4 v[140:143], v16, s[98:99] offset:48
	global_load_dwordx4 v[144:147], v16, s[98:99] offset:32
	global_load_dwordx4 v[148:151], v16, s[98:99] offset:16
	global_load_dwordx4 v[152:155], v16, s[98:99]
	global_load_dwordx4 v[156:159], v16, s[100:101] offset:48
	global_load_dwordx4 v[160:163], v16, s[100:101] offset:32
	global_load_dwordx4 v[164:167], v16, s[100:101] offset:16
	global_load_dwordx4 v[168:171], v16, s[100:101]
	global_load_dwordx4 v[172:175], v16, s[30:31] offset:48
	global_load_dwordx4 v[176:179], v16, s[30:31] offset:32
	global_load_dwordx4 v[180:183], v16, s[30:31] offset:16
	global_load_dwordx4 v[184:187], v16, s[30:31]
	s_mov_b32 s8, 0
	s_ashr_i32 s9, s8, 31
	s_lshl_b64 s[8:9], s[8:9], 3
	s_add_u32 s8, s0, s8
	s_addc_u32 s9, s1, s9
	s_waitcnt lgkmcnt(0)
	s_add_u32 s8, s8, s16
	s_addc_u32 s9, s9, s17
	s_waitcnt vmcnt(0)
	v_pk_mul_f32 v[70:71], v[44:45], v[52:53] op_sel_hi:[0,1]
	v_pk_mul_f32 v[56:57], v[44:45], v[56:57] op_sel_hi:[0,1]
	v_pk_mul_f32 v[48:49], v[44:45], v[48:49] op_sel_hi:[0,1]
	v_pk_mul_f32 v[34:35], v[44:45], v[34:35] op_sel_hi:[0,1]
	v_pk_mul_f32 v[36:37], v[44:45], v[36:37] op_sel_hi:[0,1]
	v_pk_mul_f32 v[50:51], v[44:45], v[50:51] op_sel_hi:[0,1]
	v_pk_mul_f32 v[62:63], v[44:45], v[58:59] op_sel_hi:[0,1]
	v_pk_mul_f32 v[78:79], v[44:45], v[54:55] op_sel_hi:[0,1]
	v_mov_b64_e32 v[66:67], v[140:141]
	v_mov_b64_e32 v[68:69], v[142:143]
	v_mov_b64_e32 v[72:73], v[144:145]
	v_mov_b64_e32 v[74:75], v[146:147]
	v_mov_b64_e32 v[58:59], v[148:149]
	v_mov_b64_e32 v[60:61], v[150:151]
	v_mov_b64_e32 v[44:45], v[152:153]
	v_mov_b64_e32 v[46:47], v[154:155]
	s_mov_b32 s8, 0
	s_ashr_i32 s9, s8, 31
	s_lshl_b64 s[8:9], s[8:9], 3
	s_add_u32 s8, s0, s8
	s_addc_u32 s9, s1, s9
	s_waitcnt lgkmcnt(0)
	s_add_u32 s8, s8, s18
	s_addc_u32 s9, s9, s19
	s_waitcnt vmcnt(3)
	v_pk_mul_f32 v[80:81], v[42:43], v[66:67] op_sel_hi:[0,1]
	s_waitcnt vmcnt(2)
	v_pk_mul_f32 v[64:65], v[42:43], v[72:73] op_sel_hi:[0,1]
	v_pk_mul_f32 v[72:73], v[42:43], v[74:75] op_sel_hi:[0,1]
	v_pk_mul_f32 v[86:87], v[42:43], v[68:69] op_sel_hi:[0,1]
	v_mov_b64_e32 v[88:89], v[156:157]
	v_mov_b64_e32 v[90:91], v[158:159]
	v_mov_b64_e32 v[74:75], v[160:161]
	v_mov_b64_e32 v[76:77], v[162:163]
	v_mov_b64_e32 v[66:67], v[164:165]
	v_mov_b64_e32 v[68:69], v[166:167]
	v_mov_b64_e32 v[82:83], v[168:169]
	v_mov_b64_e32 v[84:85], v[170:171]
	s_mov_b32 s8, 0
	s_ashr_i32 s9, s8, 31
	s_lshl_b64 s[8:9], s[8:9], 3
	s_add_u32 s8, s0, s8
	s_addc_u32 s9, s1, s9
	s_waitcnt vmcnt(4)
	v_pk_mul_f32 v[44:45], v[42:43], v[44:45] op_sel_hi:[0,1]
	v_pk_mul_f32 v[46:47], v[42:43], v[46:47] op_sel_hi:[0,1]
	v_pk_mul_f32 v[54:55], v[42:43], v[58:59] op_sel_hi:[0,1]
	v_pk_mul_f32 v[58:59], v[42:43], v[60:61] op_sel_hi:[0,1]
	s_waitcnt lgkmcnt(0)
	s_add_u32 s8, s8, s22
	s_addc_u32 s9, s9, s23
	v_mov_b64_e32 v[92:93], v[172:173]
	v_mov_b64_e32 v[94:95], v[174:175]
	v_mov_b64_e32 v[96:97], v[176:177]
	v_mov_b64_e32 v[98:99], v[178:179]
	v_mov_b64_e32 v[100:101], v[180:181]
	v_mov_b64_e32 v[102:103], v[182:183]
	v_mov_b64_e32 v[112:113], v[184:185]
	v_mov_b64_e32 v[114:115], v[186:187]
	s_waitcnt vmcnt(7)
	v_pk_mul_f32 v[88:89], v[40:41], v[88:89] op_sel_hi:[0,1]
	s_waitcnt vmcnt(6)
	v_pk_mul_f32 v[74:75], v[40:41], v[74:75] op_sel_hi:[0,1]
	s_waitcnt vmcnt(5)
	v_pk_mul_f32 v[60:61], v[40:41], v[66:67] op_sel_hi:[0,1]
	s_waitcnt vmcnt(4)
	v_pk_mul_f32 v[42:43], v[40:41], v[82:83] op_sel_hi:[0,1]
	v_pk_mul_f32 v[52:53], v[40:41], v[84:85] op_sel_hi:[0,1]
	v_pk_mul_f32 v[66:67], v[40:41], v[68:69] op_sel_hi:[0,1]
	v_pk_mul_f32 v[82:83], v[40:41], v[76:77] op_sel_hi:[0,1]
	v_pk_mul_f32 v[40:41], v[40:41], v[90:91] op_sel_hi:[0,1]
	s_waitcnt vmcnt(3)
	v_pk_mul_f32 v[92:93], v[38:39], v[92:93] op_sel_hi:[0,1]
	s_waitcnt vmcnt(2)
	v_pk_mul_f32 v[96:97], v[38:39], v[96:97] op_sel_hi:[0,1]
	s_waitcnt vmcnt(1)
	v_pk_mul_f32 v[84:85], v[38:39], v[100:101] op_sel_hi:[0,1]
	s_waitcnt vmcnt(0)
	v_pk_mul_f32 v[68:69], v[38:39], v[112:113] op_sel_hi:[0,1]
	v_pk_mul_f32 v[76:77], v[38:39], v[114:115] op_sel_hi:[0,1]
	v_pk_mul_f32 v[90:91], v[38:39], v[102:103] op_sel_hi:[0,1]
	v_pk_mul_f32 v[98:99], v[38:39], v[98:99] op_sel_hi:[0,1]
	v_pk_mul_f32 v[38:39], v[38:39], v[94:95] op_sel_hi:[0,1]
	v_lshlrev_b32_e32 v94, 16, v33
	v_and_b32_e32 v95, 0xffff0000, v33
	v_pk_fma_f32 v[78:79], v[78:79], v[94:95], 0 op_sel_hi:[1,1,0]
	v_lshlrev_b32_e32 v94, 16, v29
	v_and_b32_e32 v95, 0xffff0000, v29
	v_pk_fma_f32 v[78:79], v[86:87], v[94:95], v[78:79]
	v_lshlrev_b32_e32 v86, 16, v25
	v_and_b32_e32 v87, 0xffff0000, v25
	v_pk_fma_f32 v[40:41], v[40:41], v[86:87], v[78:79]
	v_lshlrev_b32_e32 v78, 16, v21
	v_and_b32_e32 v79, 0xffff0000, v21
	v_pk_fma_f32 v[38:39], v[38:39], v[78:79], v[40:41]
	v_lshlrev_b32_e32 v78, 16, v32
	v_and_b32_e32 v79, 0xffff0000, v32
	v_pk_fma_f32 v[32:33], v[70:71], v[78:79], 0 op_sel_hi:[1,1,0]
	v_lshlrev_b32_e32 v70, 16, v28
	v_and_b32_e32 v71, 0xffff0000, v28
	v_pk_fma_f32 v[28:29], v[80:81], v[70:71], v[32:33]
	v_lshlrev_b32_e32 v32, 16, v24
	v_and_b32_e32 v33, 0xffff0000, v24
	v_pk_fma_f32 v[24:25], v[88:89], v[32:33], v[28:29]
	v_lshlrev_b32_e32 v28, 16, v20
	v_and_b32_e32 v29, 0xffff0000, v20
	v_pk_fma_f32 v[20:21], v[92:93], v[28:29], v[24:25]
	v_lshlrev_b32_e32 v28, 16, v31
	v_and_b32_e32 v29, 0xffff0000, v31
	v_pk_fma_f32 v[28:29], v[62:63], v[28:29], 0 op_sel_hi:[1,1,0]
	v_lshlrev_b32_e32 v62, 16, v30
	v_and_b32_e32 v63, 0xffff0000, v30
	v_pk_fma_f32 v[30:31], v[56:57], v[62:63], 0 op_sel_hi:[1,1,0]
	v_lshlrev_b32_e32 v56, 16, v26
	v_and_b32_e32 v57, 0xffff0000, v26
	v_lshlrev_b32_e32 v32, 16, v27
	v_and_b32_e32 v33, 0xffff0000, v27
	v_pk_fma_f32 v[26:27], v[64:65], v[56:57], v[30:31]
	v_lshlrev_b32_e32 v30, 16, v22
	v_and_b32_e32 v31, 0xffff0000, v22
	v_pk_fma_f32 v[28:29], v[72:73], v[32:33], v[28:29]
	v_lshlrev_b32_e32 v32, 16, v23
	v_and_b32_e32 v33, 0xffff0000, v23
	v_pk_fma_f32 v[22:23], v[74:75], v[30:31], v[26:27]
	v_lshlrev_b32_e32 v26, 16, v18
	v_and_b32_e32 v27, 0xffff0000, v18
	v_pk_fma_f32 v[28:29], v[82:83], v[32:33], v[28:29]
	v_lshlrev_b32_e32 v32, 16, v19
	v_and_b32_e32 v33, 0xffff0000, v19
	v_pk_fma_f32 v[18:19], v[96:97], v[26:27], v[22:23]
	v_lshlrev_b32_e32 v26, 16, v15
	v_and_b32_e32 v27, 0xffff0000, v15
	v_pk_fma_f32 v[26:27], v[50:51], v[26:27], 0 op_sel_hi:[1,1,0]
	v_lshlrev_b32_e32 v50, 16, v14
	v_and_b32_e32 v51, 0xffff0000, v14
	v_mul_f32_e32 v16, 0xbfb8aa3b, v39
	v_lshlrev_b32_e32 v30, 16, v11
	v_and_b32_e32 v31, 0xffff0000, v11
	v_pk_fma_f32 v[14:15], v[48:49], v[50:51], 0 op_sel_hi:[1,1,0]
	v_lshlrev_b32_e32 v48, 16, v10
	v_and_b32_e32 v49, 0xffff0000, v10
	v_exp_f32_e32 v16, v16
	v_pk_fma_f32 v[26:27], v[58:59], v[30:31], v[26:27]
	v_lshlrev_b32_e32 v30, 16, v7
	v_and_b32_e32 v31, 0xffff0000, v7
	v_pk_fma_f32 v[10:11], v[54:55], v[48:49], v[14:15]
	v_lshlrev_b32_e32 v14, 16, v6
	v_and_b32_e32 v15, 0xffff0000, v6
	v_pk_fma_f32 v[26:27], v[66:67], v[30:31], v[26:27]
	v_lshlrev_b32_e32 v30, 16, v3
	v_and_b32_e32 v31, 0xffff0000, v3
	v_pk_fma_f32 v[6:7], v[60:61], v[14:15], v[10:11]
	v_lshlrev_b32_e32 v10, 16, v2
	v_and_b32_e32 v11, 0xffff0000, v2
	v_pk_fma_f32 v[26:27], v[90:91], v[30:31], v[26:27]
	v_pk_fma_f32 v[6:7], v[84:85], v[10:11], v[6:7]
	v_mul_f32_e32 v3, 0xbfb8aa3b, v27
	v_mul_f32_e32 v2, 0xbfb8aa3b, v7
	v_add_f32_e32 v16, 1.0, v16
	v_exp_f32_e32 v3, v3
	v_exp_f32_e32 v2, v2
	v_rcp_f32_e32 v41, v16
	v_mul_f32_e32 v16, 0xbfb8aa3b, v38
	v_exp_f32_e32 v16, v16
	v_add_f32_e32 v3, 1.0, v3
	v_add_f32_e32 v2, 1.0, v2
	v_rcp_f32_e32 v31, v3
	v_mul_f32_e32 v3, 0xbfb8aa3b, v26
	v_rcp_f32_e32 v11, v2
	v_mul_f32_e32 v2, 0xbfb8aa3b, v6
	v_add_f32_e32 v16, 1.0, v16
	v_exp_f32_e32 v3, v3
	v_exp_f32_e32 v2, v2
	v_rcp_f32_e32 v40, v16
	v_mul_f32_e32 v16, 0xbfb8aa3b, v21
	v_exp_f32_e32 v16, v16
	v_add_f32_e32 v3, 1.0, v3
	v_add_f32_e32 v2, 1.0, v2
	v_rcp_f32_e32 v30, v3
	v_rcp_f32_e32 v10, v2
	v_lshlrev_b32_e32 v2, 16, v13
	v_and_b32_e32 v3, 0xffff0000, v13
	v_add_f32_e32 v16, 1.0, v16
	v_pk_fma_f32 v[2:3], v[36:37], v[2:3], 0 op_sel_hi:[1,1,0]
	v_lshlrev_b32_e32 v14, 16, v9
	v_and_b32_e32 v15, 0xffff0000, v9
	v_rcp_f32_e32 v25, v16
	v_mul_f32_e32 v16, 0xbfb8aa3b, v20
	v_pk_fma_f32 v[2:3], v[46:47], v[14:15], v[2:3]
	v_lshlrev_b32_e32 v14, 16, v5
	v_and_b32_e32 v15, 0xffff0000, v5
	v_exp_f32_e32 v16, v16
	v_pk_fma_f32 v[2:3], v[52:53], v[14:15], v[2:3]
	v_lshlrev_b32_e32 v14, 16, v1
	v_and_b32_e32 v15, 0xffff0000, v1
	v_pk_fma_f32 v[2:3], v[76:77], v[14:15], v[2:3]
	v_add_f32_e32 v16, 1.0, v16
	v_mul_f32_e32 v1, 0xbfb8aa3b, v3
	v_exp_f32_e32 v1, v1
	v_pk_fma_f32 v[28:29], v[98:99], v[32:33], v[28:29]
	v_rcp_f32_e32 v24, v16
	v_mul_f32_e32 v16, 0xbfb8aa3b, v29
	v_exp_f32_e32 v16, v16
	v_add_f32_e32 v1, 1.0, v1
	v_rcp_f32_e32 v15, v1
	v_mul_f32_e32 v1, 0xbfb8aa3b, v2
	v_exp_f32_e32 v1, v1
	v_add_f32_e32 v16, 1.0, v16
	v_lshlrev_b32_e32 v36, 16, v12
	v_and_b32_e32 v37, 0xffff0000, v12
	v_rcp_f32_e32 v33, v16
	v_mul_f32_e32 v16, 0xbfb8aa3b, v28
	v_pk_fma_f32 v[12:13], v[34:35], v[36:37], 0 op_sel_hi:[1,1,0]
	v_lshlrev_b32_e32 v34, 16, v8
	v_and_b32_e32 v35, 0xffff0000, v8
	v_exp_f32_e32 v16, v16
	v_pk_fma_f32 v[8:9], v[44:45], v[34:35], v[12:13]
	v_lshlrev_b32_e32 v12, 16, v4
	v_and_b32_e32 v13, 0xffff0000, v4
	v_add_f32_e32 v1, 1.0, v1
	v_pk_fma_f32 v[4:5], v[42:43], v[12:13], v[8:9]
	v_lshlrev_b32_e32 v8, 16, v0
	v_and_b32_e32 v9, 0xffff0000, v0
	v_rcp_f32_e32 v14, v1
	v_pk_fma_f32 v[0:1], v[68:69], v[8:9], v[4:5]
	v_add_f32_e32 v16, 1.0, v16
	v_mul_f32_e32 v4, 0xbfb8aa3b, v1
	v_exp_f32_e32 v4, v4
	v_rcp_f32_e32 v32, v16
	v_mul_f32_e32 v16, 0xbfb8aa3b, v19
	v_exp_f32_e32 v16, v16
	v_add_f32_e32 v4, 1.0, v4
	v_rcp_f32_e32 v5, v4
	v_mul_f32_e32 v4, 0xbfb8aa3b, v0
	v_add_f32_e32 v16, 1.0, v16
	v_exp_f32_e32 v4, v4
	v_rcp_f32_e32 v23, v16
	v_mul_f32_e32 v16, 0xbfb8aa3b, v18
	v_exp_f32_e32 v16, v16
	v_add_f32_e32 v4, 1.0, v4
	v_rcp_f32_e32 v4, v4
	v_pk_mul_f32 v[2:3], v[2:3], v[14:15]
	v_add_f32_e32 v16, 1.0, v16
	v_rcp_f32_e32 v22, v16
	v_pk_mul_f32 v[0:1], v[0:1], v[4:5]
	ds_write_b128 v110, v[0:3] offset:34816
	v_pk_mul_f32 v[0:1], v[6:7], v[10:11]
	v_pk_mul_f32 v[2:3], v[26:27], v[30:31]
	ds_write_b128 v110, v[0:3] offset:34832
	v_pk_mul_f32 v[0:1], v[18:19], v[22:23]
	v_pk_mul_f32 v[2:3], v[28:29], v[32:33]
	ds_write_b128 v110, v[0:3] offset:34848
	v_pk_mul_f32 v[0:1], v[20:21], v[24:25]
	v_pk_mul_f32 v[2:3], v[38:39], v[40:41]
	v_lshl_add_u32 v44, v106, 2, 0
	ds_write_b128 v110, v[0:3] offset:34864
	s_and_saveexec_b64 s[8:9], vcc
	s_cbranch_execz .LBB0_763
	v_or_b32_e32 v0, s5, v106
	v_ashrrev_i32_e32 v1, 31, v0
	v_lshlrev_b64 v[0:1], 5, v[0:1]
	v_lshl_add_u64 v[0:1], s[42:43], 0, v[0:1]
	s_lshl_b32 s52, s37, 2
	v_lshl_add_u64 v[0:1], v[0:1], 0, s[52:53]
	v_mov_b32_e32 v2, v189
	s_nop 0
	v_mov_b32_e32 v0, v190
	s_mov_b32 s38, 0
	s_ashr_i32 s39, s38, 31
	s_lshl_b64 s[38:39], s[38:39], 3
	s_add_u32 s38, s0, s38
	s_addc_u32 s39, s1, s39
	s_or_b32 s48, s37, s35
	s_ashr_i32 s49, s48, 31
	s_lshl_b64 s[48:49], s[48:49], 2
	s_mov_b32 s2, 0xbfb8aa3b
	s_waitcnt lgkmcnt(0)
	s_add_u32 s38, s38, s48
	s_addc_u32 s39, s39, s49
	v_mov_b32_e32 v1, v191
	s_mov_b32 s38, 0
	s_ashr_i32 s39, s38, 31
	s_lshl_b64 s[38:39], s[38:39], 3
	s_add_u32 s38, s0, s38
	s_addc_u32 s39, s1, s39
	s_waitcnt lgkmcnt(0)
	s_add_u32 s38, s38, s48
	s_addc_u32 s39, s39, s49
	v_mov_b32_e32 v3, v192
	s_waitcnt vmcnt(0)
	v_mul_f32_e32 v0, 0xbfb8aa3b, v0
	v_exp_f32_e32 v0, v0
	v_mul_f32_e32 v1, 0x3fb8aa3b, v1
	v_exp_f32_e32 v1, v1
	v_add_f32_e32 v0, 1.0, v0
	v_rcp_f32_e32 v0, v0
	v_add_f32_e32 v2, v2, v3
	v_max_f32_e32 v4, 0, v2
	v_mul_f32_e64 v2, |v2|, s2
	v_exp_f32_e32 v5, v2
	s_mov_b32 s2, 0x3f2aaaab
	v_add_f32_e32 v6, 1.0, v5
	v_add_f32_e32 v2, -1.0, v6
	v_sub_f32_e32 v3, v2, v6
	v_add_f32_e32 v3, 1.0, v3
	v_sub_f32_e32 v2, v5, v2
	v_add_f32_e32 v7, v2, v3
	v_frexp_mant_f32_e32 v2, v6
	v_cmp_gt_f32_e32 vcc, s2, v2
	v_cvt_f64_f32_e32 v[2:3], v6
	v_frexp_exp_i32_f64_e32 v2, v[2:3]
	v_subbrev_co_u32_e32 v2, vcc, 0, v2, vcc
	v_sub_u32_e32 v3, 0, v2
	v_ldexp_f32 v6, v6, v3
	v_ldexp_f32 v3, v7, v3
	v_add_f32_e32 v7, -1.0, v6
	v_add_f32_e32 v8, 1.0, v7
	v_sub_f32_e32 v8, v6, v8
	v_add_f32_e32 v8, v3, v8
	v_add_f32_e32 v9, v7, v8
	v_sub_f32_e32 v7, v9, v7
	v_sub_f32_e32 v7, v8, v7
	v_add_f32_e32 v8, 1.0, v6
	v_add_f32_e32 v10, -1.0, v8
	v_sub_f32_e32 v6, v6, v10
	v_add_f32_e32 v3, v3, v6
	v_add_f32_e32 v6, v8, v3
	v_sub_f32_e32 v8, v6, v8
	v_sub_f32_e32 v3, v3, v8
	v_rcp_f32_e32 v8, v6
	v_cvt_f32_i32_e32 v2, v2
	s_mov_b32 s2, 0x3f317218
	v_mul_f32_e32 v10, v9, v8
	v_mul_f32_e32 v11, v6, v10
	v_fma_f32 v12, v10, v6, -v11
	v_fmac_f32_e32 v12, v10, v3
	v_add_f32_e32 v13, v11, v12
	v_sub_f32_e32 v14, v9, v13
	v_sub_f32_e32 v9, v9, v14
	v_sub_f32_e32 v11, v13, v11
	v_sub_f32_e32 v9, v9, v13
	v_add_f32_e32 v7, v7, v9
	v_sub_f32_e32 v9, v11, v12
	v_add_f32_e32 v7, v9, v7
	v_add_f32_e32 v9, v14, v7
	v_mul_f32_e32 v11, v8, v9
	v_mul_f32_e32 v12, v6, v11
	v_fma_f32 v6, v11, v6, -v12
	v_fmac_f32_e32 v6, v11, v3
	v_sub_f32_e32 v3, v14, v9
	v_add_f32_e32 v3, v7, v3
	v_add_f32_e32 v7, v12, v6
	v_sub_f32_e32 v13, v9, v7
	v_sub_f32_e32 v9, v9, v13
	v_sub_f32_e32 v12, v7, v12
	v_sub_f32_e32 v7, v9, v7
	v_add_f32_e32 v3, v3, v7
	v_sub_f32_e32 v6, v12, v6
	v_add_f32_e32 v3, v6, v3
	v_add_f32_e32 v6, v10, v11
	v_add_f32_e32 v3, v13, v3
	v_sub_f32_e32 v7, v6, v10
	v_mul_f32_e32 v3, v8, v3
	v_sub_f32_e32 v7, v11, v7
	v_add_f32_e32 v3, v7, v3
	v_mul_f32_e32 v10, 0x3f317218, v2
	v_add_f32_e32 v7, v6, v3
	v_fma_f32 v11, v2, s2, -v10
	v_mul_f32_e32 v8, v7, v7
	v_fmac_f32_e32 v11, 0xb102e308, v2
	v_sub_f32_e32 v2, v7, v6
	v_fmamk_f32 v9, v8, 0x3e9b6dac, v232
	v_sub_f32_e32 v2, v3, v2
	v_add_f32_e32 v3, v10, v11
	v_fmaak_f32 v9, v8, v9, 0x3f2aaada
	v_sub_f32_e32 v6, v3, v10
	v_ldexp_f32 v10, v7, 1
	v_mul_f32_e32 v7, v7, v8
	v_mul_f32_e32 v7, v7, v9
	v_add_f32_e32 v8, v10, v7
	v_sub_f32_e32 v9, v8, v10
	v_ldexp_f32 v2, v2, 1
	v_sub_f32_e32 v7, v7, v9
	v_add_f32_e32 v2, v2, v7
	v_add_f32_e32 v7, v8, v2
	v_sub_f32_e32 v8, v7, v8
	v_sub_f32_e32 v2, v2, v8
	v_add_f32_e32 v8, v3, v7
	v_sub_f32_e32 v9, v8, v3
	v_sub_f32_e32 v10, v8, v9
	v_sub_f32_e32 v6, v11, v6
	v_sub_f32_e32 v3, v3, v10
	v_sub_f32_e32 v7, v7, v9
	v_add_f32_e32 v3, v7, v3
	v_add_f32_e32 v7, v6, v2
	v_sub_f32_e32 v9, v7, v6
	v_sub_f32_e32 v10, v7, v9
	v_sub_f32_e32 v6, v6, v10
	v_sub_f32_e32 v2, v2, v9
	v_add_f32_e32 v3, v7, v3
	v_add_f32_e32 v2, v2, v6
	v_add_f32_e32 v6, v8, v3
	v_sub_f32_e32 v7, v6, v8
	v_sub_f32_e32 v3, v3, v7
	v_add_f32_e32 v2, v2, v3
	s_mov_b32 s2, 0x7f800000
	v_add_f32_e32 v2, v6, v2
	v_cmp_neq_f32_e32 vcc, s2, v5
	s_mov_b32 s2, 0x33800000
	s_nop 0
	v_cndmask_b32_e32 v2, v236, v2, vcc
	v_cmp_ngt_f32_e32 vcc, -1.0, v5
	s_nop 1
	v_cndmask_b32_e32 v2, v237, v2, vcc
	v_cmp_neq_f32_e32 vcc, -1.0, v5
	s_nop 1
	v_cndmask_b32_e32 v2, v238, v2, vcc
	v_cmp_lt_f32_e64 vcc, |v5|, s2
	s_nop 1
	v_cndmask_b32_e32 v2, v2, v5, vcc
	v_add_f32_e32 v2, v4, v2
	v_add_u32_e32 v4, -1, v234
	v_cmp_lt_i32_e32 vcc, v4, v111
	v_mul_f32_e64 v3, v2, -v1
	s_nop 0
	v_cndmask_b32_e32 v4, v4, v234, vcc
	v_lshlrev_b32_e32 v4, 2, v4
	ds_bpermute_b32 v4, v4, v3
	v_cmp_eq_u32_e32 vcc, 0, v106
	s_waitcnt lgkmcnt(0)
	v_fma_f32 v1, v2, -v1, v4
	v_add_u32_e32 v2, -2, v234
	v_cndmask_b32_e32 v1, v1, v3, vcc
	v_cmp_lt_i32_e32 vcc, v2, v111
	v_add_u32_e32 v3, 0x1cc00, v44
	s_nop 0
	v_cndmask_b32_e32 v2, v2, v234, vcc
	v_lshlrev_b32_e32 v2, 2, v2
	ds_bpermute_b32 v2, v2, v1
	v_cmp_gt_u32_e32 vcc, 2, v106
	s_waitcnt lgkmcnt(0)
	v_add_f32_e32 v2, v1, v2
	v_cndmask_b32_e32 v1, v2, v1, vcc
	v_add_u32_e32 v2, -4, v234
	v_cmp_lt_i32_e32 vcc, v2, v111
	s_nop 1
	v_cndmask_b32_e32 v2, v2, v234, vcc
	v_lshlrev_b32_e32 v2, 2, v2
	ds_bpermute_b32 v2, v2, v1
	v_cmp_gt_u32_e32 vcc, 4, v106
	s_waitcnt lgkmcnt(0)
	v_add_f32_e32 v2, v1, v2
	v_cndmask_b32_e32 v1, v2, v1, vcc
	v_add_u32_e32 v2, -8, v234
	v_cmp_lt_i32_e32 vcc, v2, v111
	s_nop 1
	v_cndmask_b32_e32 v2, v2, v234, vcc
	v_lshlrev_b32_e32 v2, 2, v2
	ds_bpermute_b32 v2, v2, v1
	v_cmp_gt_u32_e32 vcc, 8, v106
	s_waitcnt lgkmcnt(0)
	v_add_f32_e32 v2, v1, v2
	v_cndmask_b32_e32 v1, v2, v1, vcc
	v_add_u32_e32 v2, -16, v234
	v_cmp_lt_i32_e32 vcc, v2, v111
	s_nop 1
	v_cndmask_b32_e32 v2, v2, v234, vcc
	v_lshlrev_b32_e32 v2, 2, v2
	ds_bpermute_b32 v2, v2, v1
	v_cmp_gt_u32_e32 vcc, 16, v106
	s_waitcnt lgkmcnt(0)
	v_add_f32_e32 v2, v1, v2
	v_cndmask_b32_e32 v2, v2, v1, vcc
	v_subrev_u32_e32 v1, 32, v234
	v_cmp_lt_i32_e32 vcc, v1, v111
	s_nop 1
	v_cndmask_b32_e32 v1, v1, v234, vcc
	v_lshlrev_b32_e32 v1, 2, v1
	ds_bpermute_b32 v1, v1, v2
	v_cmp_gt_u32_e32 vcc, 32, v106
	s_waitcnt lgkmcnt(0)
	v_add_f32_e32 v1, v2, v1
	v_cndmask_b32_e32 v2, v1, v2, vcc
	ds_write_b32 v3, v2
	v_add_u32_e32 v2, 0x1cd00, v44
	v_cmp_eq_u32_e32 vcc, 63, v106
	ds_write_b32 v2, v0
	s_and_b64 exec, exec, vcc
	s_cbranch_execz .LBB0_763
	v_mul_f32_e32 v0, 0x3fb8aa3b, v1
	v_exp_f32_e32 v2, v0
	v_mov_b64_e32 v[0:1], s[92:93]
	global_store_dword v[0:1], v2, off
